# DIFF attention: K tile LDS swizzle also XORs byte bit 7 with key-row bit 3 (writer and reader) to remove the 2-way ds_read_b128 bank conflict
# baseline (speedup 1.0000x reference)
; __device__ __forceinline__ int v_st(int k, int c) { const int kk = (k & ~0xC) | ((k & 4) << 1) | ((k & 8) >> 1); return ((kk >> 3) * 4 + (c >> 5)) * 512 + ((kk & 7) * 32 + (c & 31)) * 2; }
; __device__ __forceinline__ int v_rd_base(int lane) { return ((lane & 3) << 3) | (((lane >> 2) & 3) << 6) | (((lane >> 4) & 1) << 5) | (((lane >> 5) & 1) << 8); }
; template <int DQK, int KW, bool DIFF, int SDEPTH, int QSP, int NBUF>
; __device__ __forceinline__ void attn_unit(const UnitP& P, char* lds) {
;     ...
;   const int sr = tid >> 4, sc = (tid & 15) * 8, vst0 = v_st(sr, sc), vst1 = v_st(32 + sr, sc);
;   const int vb0 = (int)(uintptr_t)V_lds + v_rd_base(lane);
;   int kb[4];
; #pragma unroll
;   for (int q = 0; q < 4; ++q) kb[q] = coffB + kswz<KW>(r32, q * 32 + hi * 16);
;   const unsigned voff = (unsigned)(sr * P.ldv + sc) * 2u, koff = (unsigned)(sr * P.ldk0 + sc) * 2u, koff2 = (unsigned)((tid >> 3) * P.ldk1 + (tid & 7) * 8) * 2u;
;   const int kdst0 = kswz<KW>(sr, sc * 2), kdst2 = kswz<KW>(tid >> 3, 256 + (tid & 7) * 16);
.LBB0_315:
	s_ashr_i32 s36, s33, 4
	s_ashr_i32 s10, s2, 31
	s_add_u32 s2, s2, s26
	s_mul_i32 s7, s36, 0x900
	s_addc_u32 s11, s10, 0
	s_mul_hi_i32 s6, s36, 0x900
	s_add_u32 s10, s2, s7
	s_addc_u32 s11, s11, s6
	s_add_u32 s12, s7, s8
	s_addc_u32 s13, s6, s9
	s_lshl_b64 s[6:7], s[10:11], 11
	s_lshl_b64 s[10:11], s[10:11], 12
	s_add_u32 s9, s15, s10
	s_addc_u32 s10, s16, s11
	s_lshl_b32 s2, s33, 7
	s_and_b32 s2, s2, 0x780
	s_lshl_b32 s35, s2, 1
	s_add_u32 s9, s9, s35
	s_addc_u32 s10, s10, 0
	s_add_u32 s38, s9, s40
	s_addc_u32 s39, s10, s41
	s_lshl_b64 s[12:13], s[12:13], 12
	s_add_u32 s9, s17, s12
	s_addc_u32 s11, s19, s13
	s_add_u32 s10, s9, s35
	s_addc_u32 s11, s11, 0
	v_mov_b32_e32 v176, v184
	v_mov_b32_e32 v2, v1
	v_mov_b32_e32 v3, v1
	v_mov_b32_e32 v4, v1
	v_mov_b32_e32 v5, v1
	v_mov_b32_e32 v6, v1
	v_mov_b32_e32 v7, v1
	v_mov_b32_e32 v8, v1
	v_mov_b32_e32 v9, v1
	v_mov_b32_e32 v10, v1
	v_mov_b32_e32 v11, v1
	v_mov_b32_e32 v12, v1
	v_mov_b32_e32 v13, v1
	v_mov_b32_e32 v14, v1
	v_mov_b32_e32 v15, v1
	s_add_u32 s9, s20, s12
	v_mov_b32_e32 v0, v1
	v_and_b32_e32 v162, 31, v176
	v_mov_b64_e32 v[16:17], v[14:15]
	v_lshlrev_b32_e32 v37, 3, v176
	s_addc_u32 s13, s21, s13
	v_mov_b64_e32 v[14:15], v[12:13]
	v_mov_b64_e32 v[12:13], v[10:11]
	v_mov_b64_e32 v[10:11], v[8:9]
	v_mov_b64_e32 v[8:9], v[6:7]
	v_mov_b64_e32 v[6:7], v[4:5]
	v_mov_b64_e32 v[4:5], v[2:3]
	v_mov_b64_e32 v[2:3], v[0:1]
	v_lshlrev_b32_e32 v0, 12, v162
	v_and_b32_e32 v174, 0x78, v37
	s_add_u32 s12, s9, s35
	v_lshl_add_u64 v[34:35], s[38:39], 0, v[0:1]
	v_ashrrev_i32_e32 v36, 4, v176
	v_lshlrev_b32_e32 v0, 1, v174
	s_addc_u32 s13, s13, 0
	v_lshl_or_b32 v46, v36, 12, v0
	v_mov_b32_e32 v47, v1
	v_lshl_add_u64 v[50:51], s[12:13], 0, v[46:47]
	v_add_co_u32_e32 v18, vcc, s87, v50
	v_lshl_add_u64 v[48:49], s[10:11], 0, v[46:47]
	s_nop 0
	v_addc_co_u32_e32 v19, vcc, 0, v51, vcc
	global_load_dwordx4 v[18:21], v[18:19], off
	s_nop 0
	global_load_dwordx4 v[22:25], v46, s[12:13]
	global_load_dwordx4 v[26:29], v46, s[10:11]
	v_add_co_u32_e32 v30, vcc, s87, v48
	v_bfe_u32 v175, v176, 5, 1
	s_nop 0
	v_addc_co_u32_e32 v31, vcc, 0, v49, vcc
	global_load_dwordx4 v[30:33], v[30:31], off
	v_lshlrev_b32_e32 v164, 4, v175
	v_mov_b32_e32 v165, v1
	v_lshl_add_u64 v[34:35], v[34:35], 0, v[164:165]
	global_load_dwordx4 v[142:145], v[34:35], off
	global_load_dwordx4 v[138:141], v[34:35], off offset:32
	global_load_dwordx4 v[134:137], v[34:35], off offset:64
	global_load_dwordx4 v[130:133], v[34:35], off offset:96
	v_and_b32_e32 v34, 0xfffff0, v36
	v_lshlrev_b32_e32 v35, 1, v36
	v_and_or_b32 v34, v35, 8, v34
	v_lshrrev_b32_e32 v35, 1, v36
	v_and_b32_e32 v38, 3, v36
	v_and_or_b32 v35, v35, 4, v38
	v_add_u32_e32 v38, 32, v36
	v_and_b32_e32 v39, 0xfffff0, v38
	v_lshlrev_b32_e32 v38, 1, v38
	v_and_or_b32 v38, v38, 8, v39
	v_lshrrev_b32_e32 v34, 1, v34
	v_bfe_u32 v37, v37, 5, 2
	v_lshrrev_b32_e32 v38, 1, v38
	v_ashrrev_i32_e32 v165, 8, v176
	v_or_b32_e32 v34, v34, v37
	v_or_b32_e32 v37, v38, v37
	v_lshlrev_b32_e32 v38, 8, v162
	v_lshlrev_b32_e32 v34, 9, v34
	v_lshlrev_b32_e32 v35, 6, v35
	v_lshlrev_b32_e32 v37, 9, v37
	v_lshl_add_u32 v73, v165, 7, v38
	v_and_b32_e32 v38, 48, v0
	v_or3_b32 v192, v34, v35, v38
	v_or3_b32 v193, v37, v35, v38
	v_add_u32_e32 v99, 0, v192
	v_add_u32_e32 v100, 0, v193
	v_lshlrev_b32_e32 v34, 8, v36
	v_and_b32_e32 v35, 0x70, v176
	s_waitcnt vmcnt(0)
	v_and_b32_e32 v253, 0x80, v176
	v_and_b32_e32 v252, 8, v176
	v_lshlrev_b32_e32 v252, 4, v252
	v_bitop3_b32 v194, v0, v34, v35 bitop3:0xde
	v_xor_b32_e32 v194, v253, v194
	v_add_u32_e32 v195, 0, v194
	v_lshlrev_b32_e32 v98, 4, v176
	v_and_b32_e32 v72, 0x70, v98
	v_bitop3_b32 v183, v164, v73, v72 bitop3:0xde
	v_xor_b32_e32 v183, v252, v183
	s_add_i32 s9, 0, 0x18000
	v_and_b32_e32 v177, 63, v176
	s_cmp_lg_u32 0, -1
	s_cselect_b32 s10, 0, 0
	s_lshl_b32 s8, s8, 12
	s_mov_b32 s35, 1
	s_mov_b32 s12, 2
	v_cmp_gt_u32_e64 s[38:39], 32, v177
	v_mov_b32_e32 v180, 0
	v_mov_b32_e32 v199, 1.0
	s_waitcnt vmcnt(6)
	ds_write_b128 v99, v[22:25]
	ds_write_b128 v100, v[18:21]
	v_add_co_u32_e32 v18, vcc, s91, v50
	s_waitcnt vmcnt(5)
	ds_write_b128 v195, v[26:29] offset:49152
	s_waitcnt vmcnt(4)
	ds_write_b128 v195, v[30:33] offset:57344
	v_addc_co_u32_e32 v19, vcc, 0, v51, vcc
	v_add_co_u32_e32 v20, vcc, s75, v50
	s_nop 1
	v_addc_co_u32_e32 v21, vcc, 0, v51, vcc
	global_load_dwordx4 v[34:37], v[18:19], off
	global_load_dwordx4 v[38:41], v[20:21], off
	v_add_co_u32_e32 v18, vcc, s91, v48
	s_nop 1
	v_addc_co_u32_e32 v19, vcc, 0, v49, vcc
	v_add_co_u32_e32 v20, vcc, s75, v48
	s_nop 1
	v_addc_co_u32_e32 v21, vcc, 0, v49, vcc
	global_load_dwordx4 v[42:45], v[18:19], off
	global_load_dwordx4 v[52:55], v[20:21], off
	s_waitcnt lgkmcnt(0)
	s_barrier
; template <bool FIRST> __device__ __forceinline__ void partialSM_ps(f32x16& p0, f32x16& p1, float& m_reg, float& alpha, f32x16& negm) {
;   float pmax = p0[0];
; #pragma unroll
;   for (int r = 1; r < 16; ++r) pmax = fmaxf(pmax, p0[r]);
; #pragma unroll
;   for (int r = 0; r < 16; ++r) pmax = fmaxf(pmax, p1[r]);
;   { auto rr = __builtin_amdgcn_permlane32_swap(__float_as_uint(pmax), __float_as_uint(pmax), false, false);
;     pmax = fmaxf(__uint_as_float(rr[0]), __uint_as_float(rr[1])); }
;   alpha = 1.f;
;   if (FIRST || !__builtin_expect(__all(pmax <= THRL), 1)) {
;     const float dl = FIRST ? pmax : fmaxf(pmax, 0.f); m_reg += dl;
; #pragma unroll
;     for (int r = 0; r < 16; ++r) { p0[r] -= dl; p1[r] -= dl; }
;     if (!FIRST) alpha = __builtin_amdgcn_exp2f(-dl);
; #pragma unroll
;     for (int r = 0; r < 16; ++r) negm[r] = -m_reg;
;     asm volatile("" : "+v"(negm));
;   }
; #pragma unroll
;   for (int r = 0; r < 16; ++r) p0[r] = __builtin_amdgcn_exp2f(p0[r]);
; template <int DQK, int KW, int QSP> __device__ __forceinline__ void qkt(f32x16& p0, f32x16& p1, const char* Ks, const int (&kb)[4], const bf16x8* qr, const char* qsp, const f32x16& cinit) {
;   p0 = cinit; p1 = cinit;
;   constexpr int N = DQK / 16;
;     ...
;   bf16x8 f0[2], f1[2];
;   f0[0] = KRD(0, 1); f1[0] = KRD(0, 0);
; #pragma unroll
;   for (int d0 = 0; d0 < N; ++d0) {
;     if (d0 + 1 < N) { f0[(d0 + 1) & 1] = KRD(d0 + 1, 1); f1[(d0 + 1) & 1] = KRD(d0 + 1, 0); }
;     __builtin_amdgcn_sched_barrier(0x406);
;     bf16x8 qf;
;     if constexpr (QSP > 0) { if (d0 >= N - QSP) qf = *reinterpret_cast<const bf16x8*>(qsp + (d0 - (N - QSP)) * 1024); else qf = qr[d0]; } else qf = qr[d0];
;     p0 = __builtin_amdgcn_mfma_f32_32x32x16_bf16(f0[d0 & 1], qf, p0, 0, 0, 0);
;     p1 = __builtin_amdgcn_mfma_f32_32x32x16_bf16(f1[d0 & 1], qf, p1, 0, 0, 0);
;     __builtin_amdgcn_sched_barrier(0x406); }
	v_add_u32_e32 v18, 0, v183
	ds_read_b128 v[56:59], v18 offset:49152
	ds_read_b128 v[60:63], v18 offset:57344
	v_or_b32_e32 v18, 32, v164
	v_bitop3_b32 v197, v18, v73, v72 bitop3:0xde
	v_xor_b32_e32 v197, v252, v197
	v_add_u32_e32 v18, 0, v197
	ds_read_b128 v[64:67], v18 offset:49152
	ds_read_b128 v[68:71], v18 offset:57344
	s_waitcnt vmcnt(7) lgkmcnt(0)
	v_mfma_f32_32x32x16_bf16 v[18:33], v[56:59], v[142:145], v[2:17]
	v_or_b32_e32 v56, 64, v164
	v_bitop3_b32 v196, v56, v73, v72 bitop3:0xde
	v_xor_b32_e32 v196, v252, v196
	v_mfma_f32_32x32x16_bf16 v[2:17], v[60:63], v[142:145], v[2:17]
	v_add_u32_e32 v60, 0, v196
	ds_read_b128 v[56:59], v60 offset:49152
	ds_read_b128 v[60:63], v60 offset:57344
	s_waitcnt vmcnt(6)
	v_mfma_f32_32x32x16_bf16 v[18:33], v[64:67], v[138:141], v[18:33]
	v_or_b32_e32 v64, 0x60, v164
	v_bitop3_b32 v198, v64, v73, v72 bitop3:0xde
	v_xor_b32_e32 v198, v252, v198
	v_mfma_f32_32x32x16_bf16 v[2:17], v[68:71], v[138:141], v[2:17]
	v_add_u32_e32 v68, 0, v198
	ds_read_b128 v[64:67], v68 offset:49152
	ds_read_b128 v[68:71], v68 offset:57344
	s_waitcnt vmcnt(5) lgkmcnt(3)
	v_mfma_f32_32x32x16_bf16 v[18:33], v[56:59], v[134:137], v[18:33]
	v_and_b32_e32 v56, 0x3fffffc0, v176
	v_lshl_add_u32 v178, v56, 2, s9
	s_mov_b32 s9, 0
	v_lshl_add_u32 v179, v162, 2, v178
	s_waitcnt lgkmcnt(2)
	v_mfma_f32_32x32x16_bf16 v[2:17], v[60:63], v[134:137], v[2:17]
	s_waitcnt vmcnt(4) lgkmcnt(1)
	v_mfma_f32_32x32x16_bf16 v[18:33], v[64:67], v[130:133], v[18:33]
	s_waitcnt lgkmcnt(0)
	v_mfma_f32_32x32x16_bf16 v[2:17], v[68:71], v[130:133], v[2:17]
	s_nop 9
	v_max_f32_e32 v56, v19, v19
	v_max_f32_e32 v57, v18, v18
	v_max_f32_e32 v56, v57, v56
	v_max3_f32 v56, v56, v20, v21
	v_max3_f32 v56, v56, v22, v23
	v_max3_f32 v56, v56, v24, v25
	v_max3_f32 v56, v56, v26, v27
	v_max3_f32 v56, v56, v28, v29
	v_max3_f32 v56, v56, v30, v31
	v_max3_f32 v56, v56, v32, v33
	v_max3_f32 v56, v56, v2, v3
	v_max3_f32 v56, v56, v4, v5
	v_max3_f32 v56, v56, v6, v7
	v_max3_f32 v56, v56, v8, v9
	v_max3_f32 v56, v56, v10, v11
	v_max3_f32 v56, v56, v12, v13
	v_max3_f32 v56, v56, v14, v15
	v_max3_f32 v56, v56, v16, v17
	v_mov_b32_e32 v57, v56
	s_nop 1
	v_permlane32_swap_b32_e32 v56, v57
	v_max_f32_e32 v57, v57, v57
	v_max_f32_e32 v56, v56, v56
	v_max_f32_e32 v56, v56, v57
	v_add_f32_e32 v182, 0, v56
	v_sub_f32_e32 v96, v16, v56
	v_add_co_u32_e32 v16, vcc, s51, v50
	v_sub_f32_e32 v97, v17, v56
	v_xor_b32_e32 v66, 0x80000000, v182
	v_addc_co_u32_e32 v17, vcc, 0, v51, vcc
	v_sub_f32_e32 v57, v18, v56
	v_mov_b32_e32 v67, v66
	v_mov_b32_e32 v68, v66
	v_mov_b32_e32 v69, v66
	v_mov_b32_e32 v70, v66
	v_mov_b32_e32 v71, v66
	v_mov_b32_e32 v72, v66
	v_mov_b32_e32 v73, v66
	v_mov_b32_e32 v74, v66
	v_mov_b32_e32 v75, v66
	v_mov_b32_e32 v76, v66
	v_mov_b32_e32 v77, v66
	v_mov_b32_e32 v78, v66
	v_mov_b32_e32 v79, v66
	v_mov_b32_e32 v80, v66
	v_mov_b32_e32 v81, v66
	v_add_co_u32_e32 v18, vcc, s52, v50
	v_sub_f32_e32 v58, v19, v56
	s_waitcnt vmcnt(0)
	s_nop 0
	v_addc_co_u32_e32 v19, vcc, 0, v51, vcc
	global_load_dwordx4 v[146:149], v[16:17], off
	global_load_dwordx4 v[150:153], v[18:19], off
	v_add_co_u32_e32 v16, vcc, s51, v48
	v_sub_f32_e32 v20, v20, v56
	s_nop 0
	v_addc_co_u32_e32 v17, vcc, 0, v49, vcc
	v_add_co_u32_e32 v18, vcc, s52, v48
	v_lshlrev_b32_e32 v48, 1, v176
	s_nop 0
	v_addc_co_u32_e32 v19, vcc, 0, v49, vcc
	global_load_dwordx4 v[154:157], v[16:17], off
	global_load_dwordx4 v[158:161], v[18:19], off
	v_lshlrev_b32_e32 v18, 3, v177
	v_and_b32_e32 v19, 0xc0, v98
	v_and_or_b32 v19, v18, 24, v19
	v_and_b32_e32 v48, 32, v48
	v_and_b32_e32 v18, 0x100, v18
	v_or3_b32 v18, v19, v48, v18
	v_add_u32_e32 v181, s10, v18
	s_mul_hi_i32 s10, s36, 0x900000
	s_mul_i32 s36, s36, 0x900000
	s_add_u32 s8, s36, s8
	s_addc_u32 s11, s10, 0
	s_and_b32 s10, s33, 15
	s_lshl_b32 s10, s10, 8
	v_sub_f32_e32 v21, v21, v56
	v_sub_f32_e32 v22, v22, v56
	v_sub_f32_e32 v23, v23, v56
	v_sub_f32_e32 v24, v24, v56
	v_sub_f32_e32 v25, v25, v56
	v_sub_f32_e32 v26, v26, v56
	v_sub_f32_e32 v27, v27, v56
	v_sub_f32_e32 v28, v28, v56
	v_sub_f32_e32 v29, v29, v56
	v_sub_f32_e32 v30, v30, v56
	v_sub_f32_e32 v31, v31, v56
	v_sub_f32_e32 v32, v32, v56
	v_sub_f32_e32 v33, v33, v56
	v_add_u32_e32 v18, 0x10000, v195
	s_or_b32 s8, s8, s10
	v_exp_f32_e32 v219, v57
	v_exp_f32_e32 v221, v58
	v_exp_f32_e32 v217, v20
	v_exp_f32_e32 v220, v21
	v_exp_f32_e32 v215, v22
	v_exp_f32_e32 v218, v23
	v_exp_f32_e32 v214, v24
	v_exp_f32_e32 v216, v25
	v_exp_f32_e32 v211, v26
	v_exp_f32_e32 v213, v27
	v_exp_f32_e32 v209, v28
	v_exp_f32_e32 v212, v29
	v_exp_f32_e32 v207, v30
	v_exp_f32_e32 v210, v31
	v_exp_f32_e32 v206, v32
	v_exp_f32_e32 v208, v33
	s_waitcnt vmcnt(7)
	ds_write_b128 v99, v[34:37] offset:16384
	s_waitcnt vmcnt(6)
	ds_write_b128 v100, v[38:41] offset:16384
	s_waitcnt vmcnt(5)
	ds_write_b128 v18, v[42:45]
	s_waitcnt vmcnt(4)
	ds_write_b128 v18, v[52:55] offset:8192
	s_add_u32 s10, s27, s8
	v_mov_b32_e32 v16, v1
	v_mov_b32_e32 v17, v1
	s_waitcnt lgkmcnt(0)
	s_barrier
	s_addc_u32 s11, s28, s11
	v_sub_f32_e32 v95, v15, v56
	v_sub_f32_e32 v94, v14, v56
	v_sub_f32_e32 v93, v13, v56
	v_sub_f32_e32 v92, v12, v56
	v_sub_f32_e32 v91, v11, v56
	v_sub_f32_e32 v90, v10, v56
	v_sub_f32_e32 v89, v9, v56
	v_sub_f32_e32 v88, v8, v56
	v_sub_f32_e32 v87, v7, v56
	v_sub_f32_e32 v86, v6, v56
	v_sub_f32_e32 v85, v5, v56
	v_sub_f32_e32 v84, v4, v56
	v_sub_f32_e32 v83, v3, v56
	v_sub_f32_e32 v82, v2, v56
	v_mov_b32_e32 v2, v1
	v_mov_b32_e32 v3, v1
	v_mov_b32_e32 v4, v1
	v_mov_b32_e32 v5, v1
	v_mov_b32_e32 v6, v1
	v_mov_b32_e32 v7, v1
	v_mov_b32_e32 v8, v1
	v_mov_b32_e32 v9, v1
	v_mov_b32_e32 v10, v1
	v_mov_b32_e32 v11, v1
	v_mov_b32_e32 v12, v1
	v_mov_b32_e32 v13, v1
	v_mov_b32_e32 v14, v1
	v_mov_b32_e32 v15, v1
	v_lshl_add_u64 v[166:167], s[10:11], 0, v[46:47]
	v_mov_b64_e32 v[64:65], v[16:17]
	v_mov_b64_e32 v[48:49], v[16:17]
	v_mov_b64_e32 v[32:33], v[16:17]
	v_mov_b64_e32 v[62:63], v[14:15]
	v_mov_b64_e32 v[60:61], v[12:13]
	v_mov_b64_e32 v[58:59], v[10:11]
	v_mov_b64_e32 v[56:57], v[8:9]
	v_mov_b64_e32 v[54:55], v[6:7]
	v_mov_b64_e32 v[52:53], v[4:5]
	v_mov_b64_e32 v[50:51], v[2:3]
	v_mov_b64_e32 v[46:47], v[14:15]
	v_mov_b64_e32 v[44:45], v[12:13]
	v_mov_b64_e32 v[42:43], v[10:11]
	v_mov_b64_e32 v[40:41], v[8:9]
	v_mov_b64_e32 v[38:39], v[6:7]
	v_mov_b64_e32 v[36:37], v[4:5]
	v_mov_b64_e32 v[34:35], v[2:3]
	v_mov_b64_e32 v[30:31], v[14:15]
	v_mov_b64_e32 v[28:29], v[12:13]
	v_mov_b64_e32 v[26:27], v[10:11]
	v_mov_b64_e32 v[24:25], v[8:9]
	v_mov_b64_e32 v[22:23], v[6:7]
	v_mov_b64_e32 v[20:21], v[4:5]
	v_mov_b64_e32 v[18:19], v[2:3]
